# previous stack plus merged waits in the scan-phase gates GEMM K-loop
# baseline (speedup 1.0000x reference)
.LBB0_463:
	s_add_u32 s20, s18, 0xfffc0080
	s_addc_u32 s21, s19, -1
	s_add_i32 s61, 0, 0x10000
	s_cmp_eq_u32 s60, 12
	s_cselect_b32 s23, s11, s21
	s_cselect_b32 s22, s44, s20
	v_add_u32_e32 v146, s61, v149
	s_cselect_b32 s21, s5, s59
	s_cselect_b32 s20, s45, s58
	s_add_i32 s64, 0, 0x14000
	ds_read_b128 v[152:155], v146
	ds_read_b128 v[156:159], v146 offset:1024
	ds_read_b128 v[182:185], v146 offset:2048
	ds_read_b128 v[186:189], v146 offset:3072
	v_add_u32_e32 v146, s64, v149
	ds_read_b128 v[190:193], v146
	ds_read_b128 v[194:197], v146 offset:1024
	ds_read_b128 v[198:201], v146 offset:2048
	ds_read_b128 v[202:205], v146 offset:3072
	v_lshl_add_u64 v[146:147], s[18:19], 0, v[142:143]
	s_add_i32 m0, s35, 0xc000
	ds_read_b128 v[206:209], v150
	ds_read_b128 v[210:213], v150 offset:1024
	ds_read_b128 v[214:217], v150 offset:2048
	ds_read_b128 v[218:221], v150 offset:3072
	ds_read_b128 v[222:225], v150 offset:4096
	ds_read_b128 v[226:229], v150 offset:5120
	ds_read_b128 v[230:233], v150 offset:6144
	ds_read_b128 v[234:237], v150 offset:7168
	global_load_lds_dwordx4 v[146:147], off
	v_lshl_add_u64 v[146:147], s[18:19], 0, v[136:137]
	s_add_i32 m0, s35, 0xe000
	s_nop 0
	global_load_lds_dwordx4 v[146:147], off
	s_waitcnt vmcnt(8) lgkmcnt(0)
	s_barrier
	s_setprio 1
	v_mfma_f32_16x16x32_bf16 v[126:129], v[152:155], v[206:209], v[126:129]
	v_mfma_f32_16x16x32_bf16 v[122:125], v[182:185], v[206:209], v[122:125]
	v_mfma_f32_16x16x32_bf16 v[110:113], v[152:155], v[214:217], v[110:113]
	v_mfma_f32_16x16x32_bf16 v[106:109], v[182:185], v[214:217], v[106:109]
	v_mfma_f32_16x16x32_bf16 v[94:97], v[152:155], v[222:225], v[94:97]
	v_mfma_f32_16x16x32_bf16 v[90:93], v[182:185], v[222:225], v[90:93]
	v_mfma_f32_16x16x32_bf16 v[78:81], v[152:155], v[230:233], v[78:81]
	v_mfma_f32_16x16x32_bf16 v[74:77], v[182:185], v[230:233], v[74:77]
	v_mfma_f32_16x16x32_bf16 v[126:129], v[156:159], v[210:213], v[126:129]
	v_mfma_f32_16x16x32_bf16 v[122:125], v[186:189], v[210:213], v[122:125]
	v_mfma_f32_16x16x32_bf16 v[110:113], v[156:159], v[218:221], v[110:113]
	v_mfma_f32_16x16x32_bf16 v[106:109], v[186:189], v[218:221], v[106:109]
	v_mfma_f32_16x16x32_bf16 v[94:97], v[156:159], v[226:229], v[94:97]
	v_mfma_f32_16x16x32_bf16 v[90:93], v[186:189], v[226:229], v[90:93]
	v_mfma_f32_16x16x32_bf16 v[78:81], v[156:159], v[234:237], v[78:81]
	v_mfma_f32_16x16x32_bf16 v[74:77], v[186:189], v[234:237], v[74:77]
	s_setprio 0
	s_setprio 1
	v_mfma_f32_16x16x32_bf16 v[118:121], v[190:193], v[206:209], v[118:121]
	v_mfma_f32_16x16x32_bf16 v[114:117], v[198:201], v[206:209], v[114:117]
	v_mfma_f32_16x16x32_bf16 v[102:105], v[190:193], v[214:217], v[102:105]
	v_mfma_f32_16x16x32_bf16 v[98:101], v[198:201], v[214:217], v[98:101]
	v_mfma_f32_16x16x32_bf16 v[86:89], v[190:193], v[222:225], v[86:89]
	v_mfma_f32_16x16x32_bf16 v[82:85], v[198:201], v[222:225], v[82:85]
	v_mfma_f32_16x16x32_bf16 v[70:73], v[190:193], v[230:233], v[70:73]
	v_mfma_f32_16x16x32_bf16 v[66:69], v[198:201], v[230:233], v[66:69]
	v_mfma_f32_16x16x32_bf16 v[118:121], v[194:197], v[210:213], v[118:121]
	v_mfma_f32_16x16x32_bf16 v[114:117], v[202:205], v[210:213], v[114:117]
	v_mfma_f32_16x16x32_bf16 v[102:105], v[194:197], v[218:221], v[102:105]
	v_mfma_f32_16x16x32_bf16 v[98:101], v[202:205], v[218:221], v[98:101]
	v_mfma_f32_16x16x32_bf16 v[86:89], v[194:197], v[226:229], v[86:89]
	v_mfma_f32_16x16x32_bf16 v[82:85], v[202:205], v[226:229], v[82:85]
	v_mfma_f32_16x16x32_bf16 v[70:73], v[194:197], v[234:237], v[70:73]
	v_mfma_f32_16x16x32_bf16 v[66:69], v[202:205], v[234:237], v[66:69]
	s_setprio 0
	s_barrier
	s_add_i32 s61, s61, s33
	v_lshl_add_u64 v[146:147], s[20:21], 0, v[0:1]
	s_mov_b32 m0, s61
	ds_read_b128 v[206:209], v150 offset:16384
	ds_read_b128 v[210:213], v150 offset:17408
	ds_read_b128 v[214:217], v150 offset:18432
	ds_read_b128 v[218:221], v150 offset:19456
	ds_read_b128 v[222:225], v150 offset:20480
	ds_read_b128 v[226:229], v150 offset:21504
	ds_read_b128 v[230:233], v150 offset:22528
	ds_read_b128 v[234:237], v150 offset:23552
	global_load_lds_dwordx4 v[146:147], off
	s_add_i32 m0, s61, 0x2000
	s_add_u32 s62, s20, 0x40000
	v_lshl_add_u64 v[160:161], s[20:21], 0, v[130:131]
	s_addc_u32 s63, s21, 0
	s_add_i32 s61, s64, s33
	global_load_lds_dwordx4 v[160:161], off
	v_lshl_add_u64 v[238:239], s[62:63], 0, v[0:1]
	s_mov_b32 m0, s61
	v_lshl_add_u64 v[240:241], s[22:23], 0, v[132:133]
	global_load_lds_dwordx4 v[238:239], off
	v_lshl_add_u64 v[238:239], s[62:63], 0, v[130:131]
	s_add_i32 m0, s61, 0x2000
	s_nop 0
	global_load_lds_dwordx4 v[238:239], off
	v_lshl_add_u64 v[238:239], s[22:23], 0, v[134:135]
	s_mov_b32 m0, s35
	s_nop 0
	global_load_lds_dwordx4 v[238:239], off
	s_mov_b32 m0, s36
	s_nop 0
	global_load_lds_dwordx4 v[240:241], off
	s_waitcnt vmcnt(8) lgkmcnt(0)
	s_barrier
	s_setprio 1
	v_mfma_f32_16x16x32_bf16 v[62:65], v[152:155], v[206:209], v[62:65]
	v_mfma_f32_16x16x32_bf16 v[58:61], v[182:185], v[206:209], v[58:61]
	v_mfma_f32_16x16x32_bf16 v[46:49], v[152:155], v[214:217], v[46:49]
	v_mfma_f32_16x16x32_bf16 v[42:45], v[182:185], v[214:217], v[42:45]
	v_mfma_f32_16x16x32_bf16 v[30:33], v[152:155], v[222:225], v[30:33]
	v_mfma_f32_16x16x32_bf16 v[26:29], v[182:185], v[222:225], v[26:29]
	v_mfma_f32_16x16x32_bf16 v[14:17], v[152:155], v[230:233], v[14:17]
	v_mfma_f32_16x16x32_bf16 v[10:13], v[182:185], v[230:233], v[10:13]
	v_mfma_f32_16x16x32_bf16 v[62:65], v[156:159], v[210:213], v[62:65]
	v_mfma_f32_16x16x32_bf16 v[58:61], v[186:189], v[210:213], v[58:61]
	v_mfma_f32_16x16x32_bf16 v[46:49], v[156:159], v[218:221], v[46:49]
	v_mfma_f32_16x16x32_bf16 v[42:45], v[186:189], v[218:221], v[42:45]
	v_mfma_f32_16x16x32_bf16 v[30:33], v[156:159], v[226:229], v[30:33]
	v_mfma_f32_16x16x32_bf16 v[26:29], v[186:189], v[226:229], v[26:29]
	v_mfma_f32_16x16x32_bf16 v[14:17], v[156:159], v[234:237], v[14:17]
	v_mfma_f32_16x16x32_bf16 v[10:13], v[186:189], v[234:237], v[10:13]
	s_setprio 0
	s_setprio 1
	v_mfma_f32_16x16x32_bf16 v[54:57], v[190:193], v[206:209], v[54:57]
	v_mfma_f32_16x16x32_bf16 v[50:53], v[198:201], v[206:209], v[50:53]
	v_mfma_f32_16x16x32_bf16 v[38:41], v[190:193], v[214:217], v[38:41]
	v_mfma_f32_16x16x32_bf16 v[34:37], v[198:201], v[214:217], v[34:37]
	v_mfma_f32_16x16x32_bf16 v[22:25], v[190:193], v[222:225], v[22:25]
	v_mfma_f32_16x16x32_bf16 v[18:21], v[198:201], v[222:225], v[18:21]
	v_mfma_f32_16x16x32_bf16 v[6:9], v[190:193], v[230:233], v[6:9]
	v_mfma_f32_16x16x32_bf16 v[2:5], v[198:201], v[230:233], v[2:5]
	v_mfma_f32_16x16x32_bf16 v[54:57], v[194:197], v[210:213], v[54:57]
	v_mfma_f32_16x16x32_bf16 v[50:53], v[202:205], v[210:213], v[50:53]
	v_mfma_f32_16x16x32_bf16 v[38:41], v[194:197], v[218:221], v[38:41]
	v_mfma_f32_16x16x32_bf16 v[34:37], v[202:205], v[218:221], v[34:37]
	v_mfma_f32_16x16x32_bf16 v[22:25], v[194:197], v[226:229], v[22:25]
	v_mfma_f32_16x16x32_bf16 v[18:21], v[202:205], v[226:229], v[18:21]
	v_mfma_f32_16x16x32_bf16 v[6:9], v[194:197], v[234:237], v[6:9]
	v_mfma_f32_16x16x32_bf16 v[2:5], v[202:205], v[234:237], v[2:5]
	s_setprio 0
	s_barrier
	v_add_u32_e32 v151, s66, v149
	s_add_i32 s61, 0, 0x1c000
	ds_read_b128 v[152:155], v151
	ds_read_b128 v[156:159], v151 offset:1024
	ds_read_b128 v[182:185], v151 offset:2048
	ds_read_b128 v[186:189], v151 offset:3072
	v_add_u32_e32 v151, s61, v149
	ds_read_b128 v[190:193], v151
	ds_read_b128 v[194:197], v151 offset:1024
	ds_read_b128 v[198:201], v151 offset:2048
	ds_read_b128 v[202:205], v151 offset:3072
	s_add_u32 s22, s22, 0x40000
	s_addc_u32 s23, s23, 0
	s_mov_b32 m0, s37
	v_lshl_add_u64 v[242:243], s[22:23], 0, v[134:135]
	ds_read_b128 v[206:209], v150 offset:32768
	ds_read_b128 v[210:213], v150 offset:33792
	ds_read_b128 v[214:217], v150 offset:34816
	ds_read_b128 v[218:221], v150 offset:35840
	ds_read_b128 v[222:225], v150 offset:36864
	ds_read_b128 v[226:229], v150 offset:37888
	ds_read_b128 v[230:233], v150 offset:38912
	ds_read_b128 v[234:237], v150 offset:39936
	global_load_lds_dwordx4 v[242:243], off
	v_lshl_add_u64 v[242:243], s[22:23], 0, v[132:133]
	s_mov_b32 m0, s38
	s_nop 0
	global_load_lds_dwordx4 v[242:243], off
	s_waitcnt vmcnt(8) lgkmcnt(0)
	s_barrier
	s_setprio 1
	v_mfma_f32_16x16x32_bf16 v[126:129], v[152:155], v[206:209], v[126:129]
	v_mfma_f32_16x16x32_bf16 v[122:125], v[182:185], v[206:209], v[122:125]
	v_mfma_f32_16x16x32_bf16 v[110:113], v[152:155], v[214:217], v[110:113]
	v_mfma_f32_16x16x32_bf16 v[106:109], v[182:185], v[214:217], v[106:109]
	v_mfma_f32_16x16x32_bf16 v[94:97], v[152:155], v[222:225], v[94:97]
	v_mfma_f32_16x16x32_bf16 v[90:93], v[182:185], v[222:225], v[90:93]
	v_mfma_f32_16x16x32_bf16 v[78:81], v[152:155], v[230:233], v[78:81]
	v_mfma_f32_16x16x32_bf16 v[74:77], v[182:185], v[230:233], v[74:77]
	v_mfma_f32_16x16x32_bf16 v[126:129], v[156:159], v[210:213], v[126:129]
	v_mfma_f32_16x16x32_bf16 v[122:125], v[186:189], v[210:213], v[122:125]
	v_mfma_f32_16x16x32_bf16 v[110:113], v[156:159], v[218:221], v[110:113]
	v_mfma_f32_16x16x32_bf16 v[106:109], v[186:189], v[218:221], v[106:109]
	v_mfma_f32_16x16x32_bf16 v[94:97], v[156:159], v[226:229], v[94:97]
	v_mfma_f32_16x16x32_bf16 v[90:93], v[186:189], v[226:229], v[90:93]
	v_mfma_f32_16x16x32_bf16 v[78:81], v[156:159], v[234:237], v[78:81]
	v_mfma_f32_16x16x32_bf16 v[74:77], v[186:189], v[234:237], v[74:77]
	s_setprio 0
	s_setprio 1
	v_mfma_f32_16x16x32_bf16 v[118:121], v[190:193], v[206:209], v[118:121]
	v_mfma_f32_16x16x32_bf16 v[114:117], v[198:201], v[206:209], v[114:117]
	v_mfma_f32_16x16x32_bf16 v[102:105], v[190:193], v[214:217], v[102:105]
	v_mfma_f32_16x16x32_bf16 v[98:101], v[198:201], v[214:217], v[98:101]
	v_mfma_f32_16x16x32_bf16 v[86:89], v[190:193], v[222:225], v[86:89]
	v_mfma_f32_16x16x32_bf16 v[82:85], v[198:201], v[222:225], v[82:85]
	v_mfma_f32_16x16x32_bf16 v[70:73], v[190:193], v[230:233], v[70:73]
	v_mfma_f32_16x16x32_bf16 v[66:69], v[198:201], v[230:233], v[66:69]
	v_mfma_f32_16x16x32_bf16 v[118:121], v[194:197], v[210:213], v[118:121]
	v_mfma_f32_16x16x32_bf16 v[114:117], v[202:205], v[210:213], v[114:117]
	v_mfma_f32_16x16x32_bf16 v[102:105], v[194:197], v[218:221], v[102:105]
	v_mfma_f32_16x16x32_bf16 v[98:101], v[202:205], v[218:221], v[98:101]
	v_mfma_f32_16x16x32_bf16 v[86:89], v[194:197], v[226:229], v[86:89]
	v_mfma_f32_16x16x32_bf16 v[82:85], v[202:205], v[226:229], v[82:85]
	v_mfma_f32_16x16x32_bf16 v[70:73], v[194:197], v[234:237], v[70:73]
	v_mfma_f32_16x16x32_bf16 v[66:69], v[202:205], v[234:237], v[66:69]
	s_setprio 0
	s_barrier
	s_add_i32 s22, s66, s33
	v_lshl_add_u64 v[146:147], v[146:147], 0, s[54:55]
	s_mov_b32 m0, s22
	ds_read_b128 v[206:209], v150 offset:49152
	ds_read_b128 v[210:213], v150 offset:50176
	ds_read_b128 v[214:217], v150 offset:51200
	ds_read_b128 v[218:221], v150 offset:52224
	ds_read_b128 v[222:225], v150 offset:53248
	ds_read_b128 v[226:229], v150 offset:54272
	ds_read_b128 v[230:233], v150 offset:55296
	ds_read_b128 v[234:237], v150 offset:56320
	global_load_lds_dwordx4 v[146:147], off
	s_add_i32 m0, s22, 0x2000
	s_add_u32 s20, s20, 0x40080
	v_lshl_add_u64 v[146:147], v[160:161], 0, s[54:55]
	s_addc_u32 s21, s21, 0
	s_add_i32 s22, s61, s33
	global_load_lds_dwordx4 v[146:147], off
	v_lshl_add_u64 v[146:147], s[20:21], 0, v[0:1]
	s_mov_b32 m0, s22
	s_nop 0
	global_load_lds_dwordx4 v[146:147], off
	v_lshl_add_u64 v[146:147], s[20:21], 0, v[130:131]
	s_add_i32 m0, s22, 0x2000
	s_nop 0
	global_load_lds_dwordx4 v[146:147], off
	v_lshl_add_u64 v[146:147], v[238:239], 0, s[54:55]
	s_mov_b32 m0, s40
	s_nop 0
	global_load_lds_dwordx4 v[146:147], off
	v_lshl_add_u64 v[146:147], v[240:241], 0, s[54:55]
	s_mov_b32 m0, s41
	s_nop 0
	global_load_lds_dwordx4 v[146:147], off
	s_waitcnt vmcnt(8) lgkmcnt(0)
	s_barrier
	s_setprio 1
	v_mfma_f32_16x16x32_bf16 v[62:65], v[152:155], v[206:209], v[62:65]
	v_mfma_f32_16x16x32_bf16 v[58:61], v[182:185], v[206:209], v[58:61]
	v_mfma_f32_16x16x32_bf16 v[46:49], v[152:155], v[214:217], v[46:49]
	v_mfma_f32_16x16x32_bf16 v[42:45], v[182:185], v[214:217], v[42:45]
	v_mfma_f32_16x16x32_bf16 v[30:33], v[152:155], v[222:225], v[30:33]
	v_mfma_f32_16x16x32_bf16 v[26:29], v[182:185], v[222:225], v[26:29]
	v_mfma_f32_16x16x32_bf16 v[14:17], v[152:155], v[230:233], v[14:17]
	v_mfma_f32_16x16x32_bf16 v[10:13], v[182:185], v[230:233], v[10:13]
	v_mfma_f32_16x16x32_bf16 v[62:65], v[156:159], v[210:213], v[62:65]
	v_mfma_f32_16x16x32_bf16 v[58:61], v[186:189], v[210:213], v[58:61]
	v_mfma_f32_16x16x32_bf16 v[46:49], v[156:159], v[218:221], v[46:49]
	v_mfma_f32_16x16x32_bf16 v[42:45], v[186:189], v[218:221], v[42:45]
	v_mfma_f32_16x16x32_bf16 v[30:33], v[156:159], v[226:229], v[30:33]
	v_mfma_f32_16x16x32_bf16 v[26:29], v[186:189], v[226:229], v[26:29]
	v_mfma_f32_16x16x32_bf16 v[14:17], v[156:159], v[234:237], v[14:17]
	v_mfma_f32_16x16x32_bf16 v[10:13], v[186:189], v[234:237], v[10:13]
	s_setprio 0
	s_setprio 1
	v_mfma_f32_16x16x32_bf16 v[54:57], v[190:193], v[206:209], v[54:57]
	v_mfma_f32_16x16x32_bf16 v[50:53], v[198:201], v[206:209], v[50:53]
	v_mfma_f32_16x16x32_bf16 v[38:41], v[190:193], v[214:217], v[38:41]
	v_mfma_f32_16x16x32_bf16 v[34:37], v[198:201], v[214:217], v[34:37]
	v_mfma_f32_16x16x32_bf16 v[22:25], v[190:193], v[222:225], v[22:25]
	v_mfma_f32_16x16x32_bf16 v[18:21], v[198:201], v[222:225], v[18:21]
	v_mfma_f32_16x16x32_bf16 v[6:9], v[190:193], v[230:233], v[6:9]
	v_mfma_f32_16x16x32_bf16 v[2:5], v[198:201], v[230:233], v[2:5]
	v_mfma_f32_16x16x32_bf16 v[54:57], v[194:197], v[210:213], v[54:57]
	v_mfma_f32_16x16x32_bf16 v[50:53], v[202:205], v[210:213], v[50:53]
	v_mfma_f32_16x16x32_bf16 v[38:41], v[194:197], v[218:221], v[38:41]
	v_mfma_f32_16x16x32_bf16 v[34:37], v[202:205], v[218:221], v[34:37]
	v_mfma_f32_16x16x32_bf16 v[22:25], v[194:197], v[226:229], v[22:25]
	v_mfma_f32_16x16x32_bf16 v[18:21], v[202:205], v[226:229], v[18:21]
	v_mfma_f32_16x16x32_bf16 v[6:9], v[194:197], v[234:237], v[6:9]
	v_mfma_f32_16x16x32_bf16 v[2:5], v[202:205], v[234:237], v[2:5]
	s_setprio 0
	s_barrier
	s_add_i32 s60, s60, 2
	s_add_u32 s58, s58, 0x100
	s_addc_u32 s59, s59, 0
	s_add_u32 s18, s18, 0x100
	s_addc_u32 s19, s19, 0
	s_cmp_gt_u32 s60, 13
	s_cbranch_scc0 .LBB0_463
	s_and_b64 vcc, exec, s[76:77]
	s_cbranch_vccz .LBB0_466
	s_barrier
